# pool_item epilogue: the 8 per-column scale loads issued up front with counted waits (no per-tile vmcnt(0) drain)
# speedup vs baseline: 1.0099x; 1.0004x over previous
; #define LAS __attribute__((address_space(3)))
; DI const float* INP(const Args& a, int i) { asm volatile("" : "+s"(i)); return a.in[i]; }
; DI bf16_t f2bf(float a) { return (bf16_t)(pk2(a, 0.f) & 0xffffu); }
; #define MFMA16(a, b, c) __builtin_amdgcn_mfma_f32_16x16x32_bf16((a), (b), (c), 0, 0, 0)
; DI void pool_item(LAS unsigned char* lds, const Args& a, int l, int item) {
;     ...
;     __syncthreads();
;     { const int w8 = tid >> 6, lane = tid & 63, fr = lane & 15, fq = lane >> 4;
;       bf16x8 af[4];
; #pragma unroll
;       for (int ks = 0; ks < 4; ++ks) af[ks] = *(const LAS bf16x8*)(dA + (16 * w8 + fr) * 136 + 32 * ks + 8 * fq);
;       bf16_t* MIX = (bf16_t*)(a.ws + WS_MIX); const float* psc = INP(a, 16) + l * 512 + g * 128;
; #pragma unroll
;       for (int nt = 0; nt < 8; ++nt) { f32x4 acc = {0.f, 0.f, 0.f, 0.f};
; #pragma unroll
;           for (int ks = 0; ks < 4; ++ks) { const bf16x8 bb = *(const LAS bf16x8*)(wB + (16 * nt + fr) * 136 + 32 * ks + 8 * fq); acc = MFMA16(af[ks], bb, acc); }
;           const int col = 16 * nt + fr; const float sc = psc[col];
; #pragma unroll
;           for (int reg = 0; reg < 4; ++reg) MIX[(size_t)(t0 + 16 * w8 + 4 * fq + reg) * DM + 512 + g * 128 + col] = f2bf(acc[reg] * sc); } }
.LBB0_201:
	s_nop 0
	v_cvt_pk_bf16_f32 v0, v0, v1
	v_cvt_pk_bf16_f32 v1, v2, v3
	v_or_b32_e32 v2, 7, v89
	v_lshlrev_b32_e32 v4, 1, v90
	v_mul_lo_u32 v2, v2, s47
	v_add3_u32 v2, 0, v4, v2
	v_bfe_u32 v17, v88, 4, 2
	ds_write_b64 v2, v[0:1]
	v_bfi_b32 v0, -16, v89, v88
	v_lshl_add_u32 v16, v17, 4, 0
	v_mad_u64_u32 v[0:1], s[8:9], v0, s47, v[16:17]
	s_mov_b32 s8, 16
	s_waitcnt lgkmcnt(0)
	s_barrier
	ds_read_b128 v[12:15], v0
	ds_read_b128 v[8:11], v0 offset:64
	ds_read_b128 v[4:7], v0 offset:128
	ds_read_b128 v[0:3], v0 offset:192
	s_ashr_i32 s9, s8, 31
	s_lshl_b64 s[8:9], s[8:9], 3
	s_add_u32 s8, s0, s8
	s_addc_u32 s9, s1, s9
	s_load_dwordx2 s[8:9], s[8:9], 0x0
	s_lshl_b64 s[12:13], s[10:11], 2
	v_and_b32_e32 v27, 15, v88
	v_lshlrev_b32_e32 v24, 2, v27
	v_and_b32_e32 v18, -16, v89
	s_waitcnt lgkmcnt(0)
	s_add_u32 s8, s8, s12
	s_addc_u32 s9, s9, s13
	s_lshl_b32 s12, s16, 9
	s_add_u32 s8, s8, s12
	s_addc_u32 s9, s9, 0
	global_load_dword v40, v24, s[8:9]
	global_load_dword v41, v24, s[8:9] offset:64
	global_load_dword v42, v24, s[8:9] offset:128
	global_load_dword v43, v24, s[8:9] offset:192
	global_load_dword v44, v24, s[8:9] offset:256
	global_load_dword v45, v24, s[8:9] offset:320
	global_load_dword v46, v24, s[8:9] offset:384
	global_load_dword v47, v24, s[8:9] offset:448
	v_add_u32_e32 v18, s17, v18
	v_mad_u32_u24 v25, v27, s47, v16
	v_lshl_or_b32 v26, v17, 2, v18
	ds_read_b128 v[16:19], v25 offset:34816
	ds_read_b128 v[20:23], v25 offset:34880
	s_waitcnt lgkmcnt(1)
	v_mfma_f32_16x16x32_bf16 v[16:19], v[12:15], v[16:19], 0
	s_lshl_b32 s12, s16, 8
	v_readlane_b32 s13, v254, 10
	s_add_u32 s12, s13, s12
	s_waitcnt lgkmcnt(0)
	v_mfma_f32_16x16x32_bf16 v[16:19], v[8:11], v[20:23], v[16:19]
	ds_read_b128 v[20:23], v25 offset:34944
	v_readlane_b32 s13, v254, 11
	s_addc_u32 s13, s13, 0
	s_waitcnt lgkmcnt(0)
	v_mfma_f32_16x16x32_bf16 v[16:19], v[4:7], v[20:23], v[16:19]
	ds_read_b128 v[20:23], v25 offset:35008
	v_lshlrev_b32_e32 v128, 1, v27
	v_ashrrev_i32_e32 v27, 31, v26
	s_waitcnt lgkmcnt(0)
	v_mfma_f32_16x16x32_bf16 v[20:23], v[0:3], v[20:23], v[16:19]
	v_lshl_add_u64 v[28:29], s[12:13], 0, v[128:129]
	s_waitcnt vmcnt(7)
	s_nop 5
	v_mul_f32_e32 v16, v40, v20
	v_cvt_pk_bf16_f32 v18, v16, s0
	v_lshlrev_b64 v[16:17], 11, v[26:27]
	v_lshl_add_u64 v[16:17], v[28:29], 0, v[16:17]
	global_store_short v[16:17], v18, off
	v_mul_f32_e32 v18, v40, v21
	v_cvt_pk_bf16_f32 v20, v18, s0
	v_or_b32_e32 v18, 1, v26
	v_ashrrev_i32_e32 v19, 31, v18
	v_lshlrev_b64 v[18:19], 11, v[18:19]
	v_lshl_add_u64 v[18:19], v[28:29], 0, v[18:19]
	global_store_short v[18:19], v20, off
	v_mul_f32_e32 v20, v40, v22
	v_cvt_pk_bf16_f32 v22, v20, s0
	v_or_b32_e32 v20, 2, v26
	v_ashrrev_i32_e32 v21, 31, v20
	v_lshlrev_b64 v[20:21], 11, v[20:21]
	v_lshl_add_u64 v[20:21], v[28:29], 0, v[20:21]
	global_store_short v[20:21], v22, off
	v_mul_f32_e32 v22, v40, v23
	v_cvt_pk_bf16_f32 v27, v22, s0
	v_or_b32_e32 v22, 3, v26
	v_ashrrev_i32_e32 v23, 31, v22
	v_lshlrev_b64 v[22:23], 11, v[22:23]
	v_lshl_add_u64 v[22:23], v[28:29], 0, v[22:23]
	global_store_short v[22:23], v27, off
	ds_read_b128 v[26:29], v25 offset:39168
	ds_read_b128 v[30:33], v25 offset:39232
	s_waitcnt lgkmcnt(1)
	v_mfma_f32_16x16x32_bf16 v[26:29], v[12:15], v[26:29], 0
	s_waitcnt lgkmcnt(0)
	v_mfma_f32_16x16x32_bf16 v[26:29], v[8:11], v[30:33], v[26:29]
	ds_read_b128 v[30:33], v25 offset:39296
	s_waitcnt lgkmcnt(0)
	v_mfma_f32_16x16x32_bf16 v[26:29], v[4:7], v[30:33], v[26:29]
	ds_read_b128 v[30:33], v25 offset:39360
	s_waitcnt lgkmcnt(0)
	v_mfma_f32_16x16x32_bf16 v[26:29], v[0:3], v[30:33], v[26:29]
	s_waitcnt vmcnt(10)
	s_nop 6
	v_mul_f32_e32 v26, v41, v26
	v_cvt_pk_bf16_f32 v26, v26, s0
	global_store_short v[16:17], v26, off offset:32
	v_mul_f32_e32 v26, v41, v27
	v_cvt_pk_bf16_f32 v26, v26, s0
	global_store_short v[18:19], v26, off offset:32
	v_mul_f32_e32 v26, v41, v28
	v_cvt_pk_bf16_f32 v26, v26, s0
	global_store_short v[20:21], v26, off offset:32
	v_mul_f32_e32 v26, v41, v29
	v_cvt_pk_bf16_f32 v26, v26, s0
	global_store_short v[22:23], v26, off offset:32
	ds_read_b128 v[26:29], v25 offset:43520
	ds_read_b128 v[30:33], v25 offset:43584
	s_waitcnt lgkmcnt(1)
	v_mfma_f32_16x16x32_bf16 v[26:29], v[12:15], v[26:29], 0
	s_waitcnt lgkmcnt(0)
	v_mfma_f32_16x16x32_bf16 v[26:29], v[8:11], v[30:33], v[26:29]
	ds_read_b128 v[30:33], v25 offset:43648
	s_waitcnt lgkmcnt(0)
	v_mfma_f32_16x16x32_bf16 v[26:29], v[4:7], v[30:33], v[26:29]
	ds_read_b128 v[30:33], v25 offset:43712
	s_waitcnt lgkmcnt(0)
	v_mfma_f32_16x16x32_bf16 v[26:29], v[0:3], v[30:33], v[26:29]
	s_waitcnt vmcnt(13)
	s_nop 6
	v_mul_f32_e32 v26, v42, v26
	v_cvt_pk_bf16_f32 v26, v26, s0
	global_store_short v[16:17], v26, off offset:64
	v_mul_f32_e32 v26, v42, v27
	v_cvt_pk_bf16_f32 v26, v26, s0
	global_store_short v[18:19], v26, off offset:64
	v_mul_f32_e32 v26, v42, v28
	v_cvt_pk_bf16_f32 v26, v26, s0
	global_store_short v[20:21], v26, off offset:64
	v_mul_f32_e32 v26, v42, v29
	v_cvt_pk_bf16_f32 v26, v26, s0
	global_store_short v[22:23], v26, off offset:64
	ds_read_b128 v[26:29], v25 offset:47872
	ds_read_b128 v[30:33], v25 offset:47936
	s_waitcnt lgkmcnt(1)
; #define LAS __attribute__((address_space(3)))
; DI bf16_t f2bf(float a) { return (bf16_t)(pk2(a, 0.f) & 0xffffu); }
; #define MFMA16(a, b, c) __builtin_amdgcn_mfma_f32_16x16x32_bf16((a), (b), (c), 0, 0, 0)
; DI void pool_item(LAS unsigned char* lds, const Args& a, int l, int item) {
;     ...
;       for (int nt = 0; nt < 8; ++nt) { f32x4 acc = {0.f, 0.f, 0.f, 0.f};
; #pragma unroll
;           for (int ks = 0; ks < 4; ++ks) { const bf16x8 bb = *(const LAS bf16x8*)(wB + (16 * nt + fr) * 136 + 32 * ks + 8 * fq); acc = MFMA16(af[ks], bb, acc); }
;           const int col = 16 * nt + fr; const float sc = psc[col];
; #pragma unroll
;           for (int reg = 0; reg < 4; ++reg) MIX[(size_t)(t0 + 16 * w8 + 4 * fq + reg) * DM + 512 + g * 128 + col] = f2bf(acc[reg] * sc); } }
;     __syncthreads();
	v_mfma_f32_16x16x32_bf16 v[26:29], v[12:15], v[26:29], 0
	s_waitcnt lgkmcnt(0)
	v_mfma_f32_16x16x32_bf16 v[26:29], v[8:11], v[30:33], v[26:29]
	ds_read_b128 v[30:33], v25 offset:48000
	s_waitcnt lgkmcnt(0)
	v_mfma_f32_16x16x32_bf16 v[26:29], v[4:7], v[30:33], v[26:29]
	ds_read_b128 v[30:33], v25 offset:48064
	s_waitcnt lgkmcnt(0)
	v_mfma_f32_16x16x32_bf16 v[26:29], v[0:3], v[30:33], v[26:29]
	s_waitcnt vmcnt(16)
	s_nop 6
	v_mul_f32_e32 v26, v43, v26
	v_cvt_pk_bf16_f32 v26, v26, s0
	global_store_short v[16:17], v26, off offset:96
	v_mul_f32_e32 v26, v43, v27
	v_cvt_pk_bf16_f32 v26, v26, s0
	global_store_short v[18:19], v26, off offset:96
	v_mul_f32_e32 v26, v43, v28
	v_cvt_pk_bf16_f32 v26, v26, s0
	global_store_short v[20:21], v26, off offset:96
	v_mul_f32_e32 v26, v43, v29
	v_cvt_pk_bf16_f32 v26, v26, s0
	global_store_short v[22:23], v26, off offset:96
	ds_read_b128 v[26:29], v25 offset:52224
	ds_read_b128 v[30:33], v25 offset:52288
	s_waitcnt lgkmcnt(1)
	v_mfma_f32_16x16x32_bf16 v[26:29], v[12:15], v[26:29], 0
	s_waitcnt lgkmcnt(0)
	v_mfma_f32_16x16x32_bf16 v[26:29], v[8:11], v[30:33], v[26:29]
	ds_read_b128 v[30:33], v25 offset:52352
	s_waitcnt lgkmcnt(0)
	v_mfma_f32_16x16x32_bf16 v[26:29], v[4:7], v[30:33], v[26:29]
	ds_read_b128 v[30:33], v25 offset:52416
	s_waitcnt lgkmcnt(0)
	v_mfma_f32_16x16x32_bf16 v[26:29], v[0:3], v[30:33], v[26:29]
	s_waitcnt vmcnt(19)
	s_nop 6
	v_mul_f32_e32 v26, v44, v26
	v_cvt_pk_bf16_f32 v26, v26, s0
	global_store_short v[16:17], v26, off offset:128
	v_mul_f32_e32 v26, v44, v27
	v_cvt_pk_bf16_f32 v26, v26, s0
	global_store_short v[18:19], v26, off offset:128
	v_mul_f32_e32 v26, v44, v28
	v_cvt_pk_bf16_f32 v26, v26, s0
	global_store_short v[20:21], v26, off offset:128
	v_mul_f32_e32 v26, v44, v29
	v_cvt_pk_bf16_f32 v26, v26, s0
	global_store_short v[22:23], v26, off offset:128
	ds_read_b128 v[26:29], v25 offset:56576
	ds_read_b128 v[30:33], v25 offset:56640
	s_waitcnt lgkmcnt(1)
	v_mfma_f32_16x16x32_bf16 v[26:29], v[12:15], v[26:29], 0
	s_waitcnt lgkmcnt(0)
	v_mfma_f32_16x16x32_bf16 v[26:29], v[8:11], v[30:33], v[26:29]
	ds_read_b128 v[30:33], v25 offset:56704
	s_waitcnt lgkmcnt(0)
	v_mfma_f32_16x16x32_bf16 v[26:29], v[4:7], v[30:33], v[26:29]
	ds_read_b128 v[30:33], v25 offset:56768
	s_waitcnt lgkmcnt(0)
	v_mfma_f32_16x16x32_bf16 v[26:29], v[0:3], v[30:33], v[26:29]
	s_waitcnt vmcnt(22)
	s_nop 6
	v_mul_f32_e32 v26, v45, v26
	v_cvt_pk_bf16_f32 v26, v26, s0
	global_store_short v[16:17], v26, off offset:160
	v_mul_f32_e32 v26, v45, v27
	v_cvt_pk_bf16_f32 v26, v26, s0
	global_store_short v[18:19], v26, off offset:160
	v_mul_f32_e32 v26, v45, v28
	v_cvt_pk_bf16_f32 v26, v26, s0
	global_store_short v[20:21], v26, off offset:160
	v_mul_f32_e32 v26, v45, v29
	v_cvt_pk_bf16_f32 v26, v26, s0
	global_store_short v[22:23], v26, off offset:160
	ds_read_b128 v[26:29], v25 offset:60928
	ds_read_b128 v[30:33], v25 offset:60992
	s_waitcnt lgkmcnt(1)
	v_mfma_f32_16x16x32_bf16 v[26:29], v[12:15], v[26:29], 0
	s_waitcnt lgkmcnt(0)
	v_mfma_f32_16x16x32_bf16 v[26:29], v[8:11], v[30:33], v[26:29]
	ds_read_b128 v[30:33], v25 offset:61056
	s_waitcnt lgkmcnt(0)
	v_mfma_f32_16x16x32_bf16 v[26:29], v[4:7], v[30:33], v[26:29]
	ds_read_b128 v[30:33], v25 offset:61120
	s_waitcnt lgkmcnt(0)
	v_mfma_f32_16x16x32_bf16 v[26:29], v[0:3], v[30:33], v[26:29]
	s_waitcnt vmcnt(25)
	s_nop 6
	v_mul_f32_e32 v26, v46, v26
	v_cvt_pk_bf16_f32 v26, v26, s0
	global_store_short v[16:17], v26, off offset:192
	v_mul_f32_e32 v26, v46, v27
	v_cvt_pk_bf16_f32 v26, v26, s0
	global_store_short v[18:19], v26, off offset:192
	v_mul_f32_e32 v26, v46, v28
	v_cvt_pk_bf16_f32 v26, v26, s0
	global_store_short v[20:21], v26, off offset:192
	v_mul_f32_e32 v26, v46, v29
	v_cvt_pk_bf16_f32 v26, v26, s0
	global_store_short v[22:23], v26, off offset:192
	ds_read_b128 v[26:29], v25 offset:65280
	s_waitcnt lgkmcnt(0)
	v_mfma_f32_16x16x32_bf16 v[12:15], v[12:15], v[26:29], 0
	ds_read_b128 v[26:29], v25 offset:65344
	s_waitcnt lgkmcnt(0)
	v_mfma_f32_16x16x32_bf16 v[8:11], v[8:11], v[26:29], v[12:15]
	s_nop 4
	ds_read_b128 v[12:15], v25 offset:65408
	s_waitcnt lgkmcnt(0)
	v_mfma_f32_16x16x32_bf16 v[4:7], v[4:7], v[12:15], v[8:11]
	s_nop 2
	ds_read_b128 v[8:11], v25 offset:65472
	s_waitcnt lgkmcnt(0)
	v_mfma_f32_16x16x32_bf16 v[0:3], v[0:3], v[8:11], v[4:7]
	s_nop 2
	s_mov_b64 s[8:9], 0
	s_waitcnt vmcnt(28)
	s_nop 2
	v_mul_f32_e32 v0, v47, v0
	v_cvt_pk_bf16_f32 v0, v0, s0
	global_store_short v[16:17], v0, off offset:224
	v_mul_f32_e32 v0, v47, v1
	v_cvt_pk_bf16_f32 v0, v0, s0
	global_store_short v[18:19], v0, off offset:224
	v_mul_f32_e32 v0, v47, v2
	v_cvt_pk_bf16_f32 v0, v0, s0
	global_store_short v[20:21], v0, off offset:224
	v_mul_f32_e32 v0, v47, v3
	v_cvt_pk_bf16_f32 v0, v0, s0
	global_store_short v[22:23], v0, off offset:224
	s_barrier
